# v89 + first two load segments of each tile allow the previous epilogue's stores in flight (vmcnt(8+E)); phase entry retires set-up loads with vmcnt(0)
# baseline (speedup 1.0000x reference)
; __device__ __forceinline__ int opaque_tid() { int t = (int)threadIdx.x; asm volatile("" : "+v"(t)); return t; }
; #define PG8_STAGE(bufoff, gbase, voff) do { _Pragma("unroll") for (int _i = 0; _i < 2; ++_i) \
;         __builtin_amdgcn_global_load_lds((const unsigned*)((const char*)(gbase) + (voff)[_i]), (PG8_LAS unsigned*)(lds + (bufoff) + ldsw + _i * 8192), 16, 0, 0); } while (0)
; template <class Epi, class Sched, bool ALIGN_EPI = false, bool SP2 = false>
; __device__ __forceinline__ void gemm_phase(PG8_LAS unsigned char* lds, const Gemm g, const Sched& S, const Epi& E) {
;     const int tid = opaque_tid(), wid = __builtin_amdgcn_readfirstlane(tid >> 6), lane = tid & 63, wr = wid >> 2, wc = wid & 3, fr = lane & 15, fq = lane >> 4;
;     const int K = g.K, nt = K / BK;
;     unsigned voffA[2], voffB[2];
; #pragma unroll
;     for (int i = 0; i < 2; ++i) { int R, C; stage_rc(tid * 16 + i * 8192, R, C); const int Rb = Epi::PERM ? ((R & ~31) + perm32(R & 31)) : R;
;         voffA[i] = (unsigned)(R * K + C) * 2u; voffB[i] = (unsigned)(Rb * K + C) * 2u; }
;     const size_t kstep = (size_t)(BK * 2);
;     const size_t hstep = (size_t)HALF * K * 2;
;     const size_t tstep = 2 * hstep;
;     const unsigned ldsw = (unsigned)wid * 1024u;
;     const int aoff = lds_byte(wr * 64 + fr, fq * 8), boff = lds_byte(wc * 32 + fr, fq * 8);
;     ...
;     Unit cur, nxt; int ui = 0;
;     if (!S.next(0, cur)) return;
;     f32x4 acc[2][2][4][2];
; #pragma unroll
;     for (int a = 0; a < 2; ++a)
; #pragma unroll
;         for (int b = 0; b < 2; ++b)
; #pragma unroll
;             for (int m = 0; m < 4; ++m)
; #pragma unroll
;                 for (int n = 0; n < 2; ++n) acc[a][b][m][n] = (f32x4){0.f, 0.f, 0.f, 0.f};
;     bf16x8 At[4][2], B0[2][2], B1[2][2];
;     const char* cA = (const char*)g.A + (size_t)cur.pm * tstep; const char* cB = (const char*)g.Bt + (size_t)cur.pn * tstep;
;     S.a_ready(cur);
;     if constexpr (SP2) {
;         PG8_STAGE(PG8_SB(0, 0), cB, voffB); PG8_STAGE(PG8_SB(0, 1), cB + hstep, voffB); PG8_STAGE(PG8_SA(0, 0), cA, voffA); PG8_STAGE(PG8_SA(0, 1), cA + hstep, voffA);
;         if (wr == 1) PG8_BAR;
;         PG8_WAIT_V(2); PG8_BAR;
;         PG8_STAGE(PG8_SB(1, 0), cB + kstep, voffB); PG8_STAGE(PG8_SA(1, 0), cA + kstep, voffA); PG8_STAGE(PG8_SB(1, 1), cB + hstep + kstep, voffB);
;         PG8_WAIT_V(6); PG8_BAR;
.LBB0_94:
	s_add_u32 s48, s4, 0xa400000
	s_addc_u32 s49, s5, 0
	s_lshl_b32 s7, s78, 7
	s_and_b32 s7, s7, 0x100
	s_add_u32 s22, s16, s7
	s_addc_u32 s23, s17, 0
	s_add_u32 s7, s14, s7
	s_addc_u32 s11, s15, 0
	s_and_b32 s21, s19, 3
	s_add_i32 m0, s42, 0x18000
	v_lshl_add_u64 v[10:11], v[10:11], 0, s[82:83]
	s_lshl_b32 s16, s20, 13
	s_lshl_b32 s17, s21, 12
	s_waitcnt vmcnt(2)
	s_barrier
	global_load_lds_dwordx4 v[10:11], off
	v_lshl_add_u64 v[8:9], v[8:9], 0, s[82:83]
	s_add_i32 m0, s42, 0x1a000
	s_add_i32 s50, s42, 0x8000
	s_add_i32 s51, s42, 0xa000
	global_load_lds_dwordx4 v[8:9], off
	v_lshl_add_u64 v[4:5], v[4:5], 0, s[82:83]
	s_mov_b32 m0, s50
	s_add_u32 s14, s28, 0x40080
	global_load_lds_dwordx4 v[4:5], off
	v_lshl_add_u64 v[4:5], v[6:7], 0, s[82:83]
	s_mov_b32 m0, s51
	s_addc_u32 s15, s29, 0
	global_load_lds_dwordx4 v[4:5], off
	s_add_i32 m0, s42, 0x1c000
	v_lshl_add_u64 v[4:5], s[14:15], 0, v[168:169]
	global_load_lds_dwordx4 v[4:5], off
	v_lshl_add_u64 v[4:5], s[14:15], 0, v[172:173]
	s_add_i32 m0, s42, 0x1e000
	v_bfe_u32 v6, v12, 4, 2
	global_load_lds_dwordx4 v[4:5], off
	v_and_b32_e32 v5, 15, v12
	v_lshlrev_b32_e32 v4, 4, v6
	v_lshlrev_b32_e32 v7, 2, v12
	v_lshl_or_b32 v3, s20, 6, v5
	v_lshl_or_b32 v5, v5, 6, v4
	v_and_b32_e32 v7, 32, v7
	s_cmpk_lt_u32 s18, 0x100
	v_bitop3_b32 v9, v5, s16, v7 bitop3:0xde
	v_bitop3_b32 v204, v5, s17, v7 bitop3:0xde
	v_add_u32_e32 v204, 0x10000, v204
	s_cselect_b64 s[14:15], -1, 0
	s_ashr_i32 s52, s34, 31
	v_mov_b32_e32 v5, v2
	s_cmp_lg_u32 s3, 0
	v_lshl_add_u64 v[4:5], s[4:5], 0, v[4:5]
	s_mov_b64 s[2:3], 0x1a400000
	v_lshl_add_u64 v[176:177], v[4:5], 0, s[2:3]
	v_lshlrev_b32_e32 v5, 14, v13
	v_lshlrev_b32_e32 v8, 3, v6
	v_lshlrev_b32_e32 v6, 5, v6
	v_mov_b32_e32 v7, v2
	v_and_b32_e32 v5, 0xffff8000, v5
	v_lshl_add_u64 v[174:175], s[22:23], 0, v[6:7]
	v_lshl_add_u32 v5, v14, 11, v5
	v_and_b32_e32 v6, 1, v13
	v_lshl_or_b32 v5, v6, 6, v5
	v_lshl_add_u32 v178, v15, 1, v5
	v_lshlrev_b32_e32 v5, 14, v16
	v_and_b32_e32 v5, 0xffff8000, v5
	s_waitcnt vmcnt(6)
	s_cselect_b64 s[16:17], -1, 0
	s_sub_u32 s18, s7, s22
	v_lshl_add_u32 v5, v17, 11, v5
	v_and_b32_e32 v6, 1, v16
	s_subb_u32 s19, s11, s23
	v_lshl_or_b32 v4, s21, 6, v8
	v_lshl_or_b32 v5, v6, 6, v5
	s_mov_b32 s72, 0
	s_ashr_i64 s[18:19], s[18:19], 2
	v_mov_b32_e32 v179, v2
	v_lshl_add_u32 v180, v18, 1, v5
	v_mov_b32_e32 v181, v2
	v_add_u32_e32 v205, 0, v9
	v_lshlrev_b32_e32 v206, 1, v4
	s_waitcnt vmcnt(0)
	s_barrier
	s_branch .LBB0_97

; #define PG8_STAGE(bufoff, gbase, voff) do { _Pragma("unroll") for (int _i = 0; _i < 2; ++_i) \
;         __builtin_amdgcn_global_load_lds((const unsigned*)((const char*)(gbase) + (voff)[_i]), (PG8_LAS unsigned*)(lds + (bufoff) + ldsw + _i * 8192), 16, 0, 0); } while (0)
; #define PG8_LDA(dst, b, h) do { _Pragma("unroll") for (int m = 0; m < 4; ++m) _Pragma("unroll") for (int k = 0; k < 2; ++k) dst[m][k] = *(const PG8_LAS bf16x8*)(lds + PG8_SA(b, h) + aoff + m * 2048 + k * 1024); } while (0)
; #define PG8_LDB(dst, b, h) do { _Pragma("unroll") for (int n = 0; n < 2; ++n) _Pragma("unroll") for (int k = 0; k < 2; ++k) dst[n][k] = *(const PG8_LAS bf16x8*)(lds + PG8_SB(b, h) + boff + n * 2048 + k * 1024); } while (0)
; #define PG8_MMA(ai, bj, At, Bt) do { __builtin_amdgcn_s_setprio(1); _Pragma("unroll") for (int m = 0; m < 4; ++m) _Pragma("unroll") for (int n = 0; n < 2; ++n) _Pragma("unroll") for (int k = 0; k < 2; ++k) \
;         acc[ai][bj][m][n] = __builtin_amdgcn_mfma_f32_16x16x32_bf16(Bt[n][k], At[m][k], acc[ai][bj][m][n], 0, 0, 0); __builtin_amdgcn_s_setprio(0); } while (0)
; #define PG8_WAIT_V(n) asm volatile("s_waitcnt vmcnt(" #n ")" ::: "memory")
; #define PG8_WAIT_L(n) asm volatile("s_waitcnt lgkmcnt(" #n ")" ::: "memory")
; #define PG8_BAR __builtin_amdgcn_s_barrier()
; template <class Epi, class Sched, bool ALIGN_EPI = false, bool SP2 = false>
; __device__ __forceinline__ void gemm_phase(PG8_LAS unsigned char* lds, const Gemm g, const Sched& S, const Epi& E) {
;     ...
;         const bool has_next = S.next(ui + 1, nxt);
;         const char* nA = has_next ? (const char*)g.A + (size_t)nxt.pm * tstep : cA; const char* nB = has_next ? (const char*)g.Bt + (size_t)nxt.pn * tstep : cB;
;         for (int t = 0; t < nt; t += 2) {
;             const bool last = (t == nt - 2);
;             const char* a1 = cA + (size_t)(t + 1) * kstep;
;             const char* a2 = last ? nA : cA + (size_t)(t + 2) * kstep; const char* b2 = last ? nB : cB + (size_t)(t + 2) * kstep;
;             const char* a3 = a2 + kstep; const char* b3 = b2 + kstep;
;             if (last && has_next) S.a_ready(nxt);
;             if constexpr (SP2) {
;             PG8_LDB(B0, 0, 0); PG8_LDB(B1, 0, 1); PG8_SCHED; PG8_LDA(At, 0, 0); PG8_STAGE(PG8_SA(1, 1), a1 + hstep, voffA);
;             PG8_WAIT_V(8); PG8_WAIT_L(0); PG8_BAR; PG8_MMA(0, 0, At, B0); PG8_MMA(0, 1, At, B1); PG8_BAR; PG8_SCHED;
.LBB0_99:
	s_ashr_i32 s21, s20, 31
	s_lshl_b64 s[24:25], s[20:21], 19
	s_add_u32 s24, s35, s24
	s_addc_u32 s25, s38, s25
	s_and_b64 s[26:27], s[4:5], exec
	s_cselect_b32 s3, s25, s9
	s_cselect_b32 s7, s24, s8
	s_ashr_i32 s23, s22, 31
	s_lshl_b64 s[26:27], s[22:23], 19
	s_add_u32 s26, s39, s26
	s_addc_u32 s27, s40, s27
	s_and_b64 s[30:31], s[4:5], exec
	s_cselect_b32 s11, s27, s29
	s_cselect_b32 s21, s26, s28
	s_add_u32 s8, s8, 0x40080
	s_addc_u32 s9, s9, 0
	s_add_u32 s23, s28, 0x100
	s_addc_u32 s44, s29, 0
	s_mov_b32 s45, -2
	s_add_u32 s28, s8, 0xfffc0080
	s_addc_u32 s29, s9, -1
	s_cmp_eq_u32 s45, 12
	s_cselect_b32 s31, s3, s29
	s_cselect_b32 s30, s7, s28
	s_cselect_b32 s29, s11, s44
	s_cselect_b32 s28, s21, s23
	ds_read_b128 v[132:135], v204
	ds_read_b128 v[136:139], v204 offset:1024
	ds_read_b128 v[140:143], v204 offset:2048
	ds_read_b128 v[144:147], v204 offset:3072
	ds_read_b128 v[148:151], v204 offset:16384
	ds_read_b128 v[152:155], v204 offset:17408
	ds_read_b128 v[156:159], v204 offset:18432
	ds_read_b128 v[160:163], v204 offset:19456
	v_lshl_add_u64 v[194:195], s[8:9], 0, v[178:179]
	s_add_i32 m0, s42, 0xc000
	ds_read_b128 v[164:167], v205
	ds_read_b128 v[182:185], v205 offset:1024
	ds_read_b128 v[186:189], v205 offset:2048
	ds_read_b128 v[190:193], v205 offset:3072
	ds_read_b128 v[208:211], v205 offset:4096
	ds_read_b128 v[212:215], v205 offset:5120
	ds_read_b128 v[216:219], v205 offset:6144
	ds_read_b128 v[220:223], v205 offset:7168
	global_load_lds_dwordx4 v[194:195], off
	s_add_i32 m0, s42, 0xe000
	v_lshl_add_u64 v[194:195], s[8:9], 0, v[180:181]
	global_load_lds_dwordx4 v[194:195], off
	s_waitcnt vmcnt(24) lgkmcnt(0)
	s_barrier
	s_setprio 1
	v_mfma_f32_16x16x32_bf16 v[128:131], v[132:135], v[164:167], 0
	v_mfma_f32_16x16x32_bf16 v[124:127], v[140:143], v[164:167], 0
	v_mfma_f32_16x16x32_bf16 v[112:115], v[132:135], v[186:189], 0
	v_mfma_f32_16x16x32_bf16 v[108:111], v[140:143], v[186:189], 0
	v_mfma_f32_16x16x32_bf16 v[96:99], v[132:135], v[208:211], 0
	v_mfma_f32_16x16x32_bf16 v[92:95], v[140:143], v[208:211], 0
	v_mfma_f32_16x16x32_bf16 v[80:83], v[132:135], v[216:219], 0
	v_mfma_f32_16x16x32_bf16 v[76:79], v[140:143], v[216:219], 0
	v_mfma_f32_16x16x32_bf16 v[128:131], v[136:139], v[182:185], v[128:131]
	v_mfma_f32_16x16x32_bf16 v[124:127], v[144:147], v[182:185], v[124:127]
	v_mfma_f32_16x16x32_bf16 v[112:115], v[136:139], v[190:193], v[112:115]
	v_mfma_f32_16x16x32_bf16 v[108:111], v[144:147], v[190:193], v[108:111]
	v_mfma_f32_16x16x32_bf16 v[96:99], v[136:139], v[212:215], v[96:99]
	v_mfma_f32_16x16x32_bf16 v[92:95], v[144:147], v[212:215], v[92:95]
	v_mfma_f32_16x16x32_bf16 v[80:83], v[136:139], v[220:223], v[80:83]
	v_mfma_f32_16x16x32_bf16 v[76:79], v[144:147], v[220:223], v[76:79]
	s_setprio 0
	s_setprio 1
	v_mfma_f32_16x16x32_bf16 v[120:123], v[148:151], v[164:167], 0
	v_mfma_f32_16x16x32_bf16 v[116:119], v[156:159], v[164:167], 0
	v_mfma_f32_16x16x32_bf16 v[104:107], v[148:151], v[186:189], 0
	v_mfma_f32_16x16x32_bf16 v[100:103], v[156:159], v[186:189], 0
	v_mfma_f32_16x16x32_bf16 v[88:91], v[148:151], v[208:211], 0
	v_mfma_f32_16x16x32_bf16 v[84:87], v[156:159], v[208:211], 0
	v_mfma_f32_16x16x32_bf16 v[72:75], v[148:151], v[216:219], 0
	v_mfma_f32_16x16x32_bf16 v[68:71], v[156:159], v[216:219], 0
	v_mfma_f32_16x16x32_bf16 v[120:123], v[152:155], v[182:185], v[120:123]
	v_mfma_f32_16x16x32_bf16 v[116:119], v[160:163], v[182:185], v[116:119]
	v_mfma_f32_16x16x32_bf16 v[104:107], v[152:155], v[190:193], v[104:107]
	v_mfma_f32_16x16x32_bf16 v[100:103], v[160:163], v[190:193], v[100:103]
	v_mfma_f32_16x16x32_bf16 v[88:91], v[152:155], v[212:215], v[88:91]
	v_mfma_f32_16x16x32_bf16 v[84:87], v[160:163], v[212:215], v[84:87]
	v_mfma_f32_16x16x32_bf16 v[72:75], v[152:155], v[220:223], v[72:75]
	v_mfma_f32_16x16x32_bf16 v[68:71], v[160:163], v[220:223], v[68:71]
	s_setprio 0
	s_barrier
; #define PG8_STAGE(bufoff, gbase, voff) do { _Pragma("unroll") for (int _i = 0; _i < 2; ++_i) \
;         __builtin_amdgcn_global_load_lds((const unsigned*)((const char*)(gbase) + (voff)[_i]), (PG8_LAS unsigned*)(lds + (bufoff) + ldsw + _i * 8192), 16, 0, 0); } while (0)
; #define PG8_LDA(dst, b, h) do { _Pragma("unroll") for (int m = 0; m < 4; ++m) _Pragma("unroll") for (int k = 0; k < 2; ++k) dst[m][k] = *(const PG8_LAS bf16x8*)(lds + PG8_SA(b, h) + aoff + m * 2048 + k * 1024); } while (0)
; #define PG8_MMA(ai, bj, At, Bt) do { __builtin_amdgcn_s_setprio(1); _Pragma("unroll") for (int m = 0; m < 4; ++m) _Pragma("unroll") for (int n = 0; n < 2; ++n) _Pragma("unroll") for (int k = 0; k < 2; ++k) \
;         acc[ai][bj][m][n] = __builtin_amdgcn_mfma_f32_16x16x32_bf16(Bt[n][k], At[m][k], acc[ai][bj][m][n], 0, 0, 0); __builtin_amdgcn_s_setprio(0); } while (0)
; #define PG8_WAIT_V(n) asm volatile("s_waitcnt vmcnt(" #n ")" ::: "memory")
; #define PG8_WAIT_L(n) asm volatile("s_waitcnt lgkmcnt(" #n ")" ::: "memory")
; #define PG8_BAR __builtin_amdgcn_s_barrier()
; #define PG8_SCHED __builtin_amdgcn_sched_barrier(0)
; template <class Epi, class Sched, bool ALIGN_EPI = false, bool SP2 = false>
; __device__ __forceinline__ void gemm_phase(PG8_LAS unsigned char* lds, const Gemm g, const Sched& S, const Epi& E) {
;     ...
;             PG8_LDA(At, 0, 1); PG8_STAGE(PG8_SB(0, 0), b2, voffB); PG8_STAGE(PG8_SB(0, 1), b2 + hstep, voffB); PG8_STAGE(PG8_SA(0, 0), a2, voffA);
;             PG8_WAIT_V(8); PG8_WAIT_L(0); PG8_BAR; PG8_MMA(1, 0, At, B0); PG8_MMA(1, 1, At, B1); PG8_BAR; PG8_SCHED;
	v_lshl_add_u64 v[194:195], s[28:29], 0, v[168:169]
	s_add_i32 m0, s41, 0x10000
	ds_read_b128 v[164:167], v205 offset:16384
	ds_read_b128 v[182:185], v205 offset:17408
	ds_read_b128 v[186:189], v205 offset:18432
	ds_read_b128 v[190:193], v205 offset:19456
	ds_read_b128 v[208:211], v205 offset:20480
	ds_read_b128 v[212:215], v205 offset:21504
	ds_read_b128 v[216:219], v205 offset:22528
	ds_read_b128 v[220:223], v205 offset:23552
	global_load_lds_dwordx4 v[194:195], off
	s_add_i32 m0, s41, 0x12000
	s_add_u32 s54, s28, 0x40000
	v_lshl_add_u64 v[202:203], s[28:29], 0, v[172:173]
	s_addc_u32 s55, s29, 0
	global_load_lds_dwordx4 v[202:203], off
	v_lshl_add_u64 v[224:225], s[54:55], 0, v[168:169]
	s_add_i32 m0, s41, 0x14000
	v_lshl_add_u64 v[226:227], s[30:31], 0, v[170:171]
	global_load_lds_dwordx4 v[224:225], off
	s_add_i32 m0, s41, 0x16000
	v_lshl_add_u64 v[224:225], s[54:55], 0, v[172:173]
	global_load_lds_dwordx4 v[224:225], off
	s_mov_b32 m0, s42
	v_lshl_add_u64 v[224:225], s[30:31], 0, v[0:1]
	global_load_lds_dwordx4 v[224:225], off
	s_mov_b32 m0, s43
	s_add_i32 s53, 0, 0x18000
	global_load_lds_dwordx4 v[226:227], off
	s_waitcnt vmcnt(24) lgkmcnt(0)
	s_barrier
	s_setprio 1
	v_mfma_f32_16x16x32_bf16 v[64:67], v[132:135], v[164:167], 0
	v_mfma_f32_16x16x32_bf16 v[60:63], v[140:143], v[164:167], 0
	v_mfma_f32_16x16x32_bf16 v[48:51], v[132:135], v[186:189], 0
	v_mfma_f32_16x16x32_bf16 v[44:47], v[140:143], v[186:189], 0
	v_mfma_f32_16x16x32_bf16 v[32:35], v[132:135], v[208:211], 0
	v_mfma_f32_16x16x32_bf16 v[28:31], v[140:143], v[208:211], 0
	v_mfma_f32_16x16x32_bf16 v[16:19], v[132:135], v[216:219], 0
	v_mfma_f32_16x16x32_bf16 v[12:15], v[140:143], v[216:219], 0
	v_mfma_f32_16x16x32_bf16 v[64:67], v[136:139], v[182:185], v[64:67]
	v_mfma_f32_16x16x32_bf16 v[60:63], v[144:147], v[182:185], v[60:63]
	v_mfma_f32_16x16x32_bf16 v[48:51], v[136:139], v[190:193], v[48:51]
	v_mfma_f32_16x16x32_bf16 v[44:47], v[144:147], v[190:193], v[44:47]
	v_mfma_f32_16x16x32_bf16 v[32:35], v[136:139], v[212:215], v[32:35]
	v_mfma_f32_16x16x32_bf16 v[28:31], v[144:147], v[212:215], v[28:31]
	v_mfma_f32_16x16x32_bf16 v[16:19], v[136:139], v[220:223], v[16:19]
	v_mfma_f32_16x16x32_bf16 v[12:15], v[144:147], v[220:223], v[12:15]
	s_setprio 0
	s_setprio 1
	v_mfma_f32_16x16x32_bf16 v[56:59], v[148:151], v[164:167], 0
	v_mfma_f32_16x16x32_bf16 v[52:55], v[156:159], v[164:167], 0
	v_mfma_f32_16x16x32_bf16 v[40:43], v[148:151], v[186:189], 0
	v_mfma_f32_16x16x32_bf16 v[36:39], v[156:159], v[186:189], 0
	v_mfma_f32_16x16x32_bf16 v[24:27], v[148:151], v[208:211], 0
	v_mfma_f32_16x16x32_bf16 v[20:23], v[156:159], v[208:211], 0
	v_mfma_f32_16x16x32_bf16 v[8:11], v[148:151], v[216:219], 0
	v_mfma_f32_16x16x32_bf16 v[4:7], v[156:159], v[216:219], 0
	v_mfma_f32_16x16x32_bf16 v[56:59], v[152:155], v[182:185], v[56:59]
	v_mfma_f32_16x16x32_bf16 v[52:55], v[160:163], v[182:185], v[52:55]
	v_mfma_f32_16x16x32_bf16 v[40:43], v[152:155], v[190:193], v[40:43]
	v_mfma_f32_16x16x32_bf16 v[36:39], v[160:163], v[190:193], v[36:39]
	v_mfma_f32_16x16x32_bf16 v[24:27], v[152:155], v[212:215], v[24:27]
	v_mfma_f32_16x16x32_bf16 v[20:23], v[160:163], v[212:215], v[20:23]
	v_mfma_f32_16x16x32_bf16 v[8:11], v[152:155], v[220:223], v[8:11]
	v_mfma_f32_16x16x32_bf16 v[4:7], v[160:163], v[220:223], v[4:7]
	s_setprio 0
	s_barrier
	s_branch .Lkmid_0

; #define PG8_STAGE(bufoff, gbase, voff) do { _Pragma("unroll") for (int _i = 0; _i < 2; ++_i) \
;         __builtin_amdgcn_global_load_lds((const unsigned*)((const char*)(gbase) + (voff)[_i]), (PG8_LAS unsigned*)(lds + (bufoff) + ldsw + _i * 8192), 16, 0, 0); } while (0)
; #define PG8_LDA(dst, b, h) do { _Pragma("unroll") for (int m = 0; m < 4; ++m) _Pragma("unroll") for (int k = 0; k < 2; ++k) dst[m][k] = *(const PG8_LAS bf16x8*)(lds + PG8_SA(b, h) + aoff + m * 2048 + k * 1024); } while (0)
; #define PG8_LDB(dst, b, h) do { _Pragma("unroll") for (int n = 0; n < 2; ++n) _Pragma("unroll") for (int k = 0; k < 2; ++k) dst[n][k] = *(const PG8_LAS bf16x8*)(lds + PG8_SB(b, h) + boff + n * 2048 + k * 1024); } while (0)
; #define PG8_MMA(ai, bj, At, Bt) do { __builtin_amdgcn_s_setprio(1); _Pragma("unroll") for (int m = 0; m < 4; ++m) _Pragma("unroll") for (int n = 0; n < 2; ++n) _Pragma("unroll") for (int k = 0; k < 2; ++k) \
;         acc[ai][bj][m][n] = __builtin_amdgcn_mfma_f32_16x16x32_bf16(Bt[n][k], At[m][k], acc[ai][bj][m][n], 0, 0, 0); __builtin_amdgcn_s_setprio(0); } while (0)
; #define PG8_WAIT_V(n) asm volatile("s_waitcnt vmcnt(" #n ")" ::: "memory")
; #define PG8_WAIT_L(n) asm volatile("s_waitcnt lgkmcnt(" #n ")" ::: "memory")
; #define PG8_BAR __builtin_amdgcn_s_barrier()
; template <class Epi, class Sched, bool ALIGN_EPI = false, bool SP2 = false>
; __device__ __forceinline__ void gemm_phase(PG8_LAS unsigned char* lds, const Gemm g, const Sched& S, const Epi& E) {
;     ...
;         const bool has_next = S.next(ui + 1, nxt);
;         const char* nA = has_next ? (const char*)g.A + (size_t)nxt.pm * tstep : cA; const char* nB = has_next ? (const char*)g.Bt + (size_t)nxt.pn * tstep : cB;
;         for (int t = 0; t < nt; t += 2) {
;             const bool last = (t == nt - 2);
;             const char* a1 = cA + (size_t)(t + 1) * kstep;
;             const char* a2 = last ? nA : cA + (size_t)(t + 2) * kstep; const char* b2 = last ? nB : cB + (size_t)(t + 2) * kstep;
;             const char* a3 = a2 + kstep; const char* b3 = b2 + kstep;
;             if (last && has_next) S.a_ready(nxt);
;             if constexpr (SP2) {
;             PG8_LDB(B0, 0, 0); PG8_LDB(B1, 0, 1); PG8_SCHED; PG8_LDA(At, 0, 0); PG8_STAGE(PG8_SA(1, 1), a1 + hstep, voffA);
;             PG8_WAIT_V(8); PG8_WAIT_L(0); PG8_BAR; PG8_MMA(0, 0, At, B0); PG8_MMA(0, 1, At, B1); PG8_BAR; PG8_SCHED;
.LBB0_328:
	s_ashr_i32 s17, s16, 31
	s_lshl_b64 s[20:21], s[16:17], 19
	s_add_u32 s20, s37, s20
	s_addc_u32 s21, s38, s21
	s_and_b64 s[22:23], s[6:7], exec
	s_cselect_b32 s3, s21, s29
	s_cselect_b32 s17, s20, s28
	s_ashr_i32 s19, s18, 31
	s_lshl_b64 s[22:23], s[18:19], 19
	s_add_u32 s22, s39, s22
	s_addc_u32 s23, s40, s23
	s_and_b64 s[34:35], s[6:7], exec
	s_cselect_b32 s19, s23, s31
	s_cselect_b32 s25, s22, s30
	s_add_u32 s28, s28, 0x40080
	s_addc_u32 s29, s29, 0
	s_add_u32 s27, s30, 0x100
	s_addc_u32 s44, s31, 0
	s_mov_b32 s45, -2
	s_add_u32 s30, s28, 0xfffc0080
	s_addc_u32 s31, s29, -1
	s_cmp_eq_u32 s45, 12
	s_cselect_b32 s35, s3, s31
	s_cselect_b32 s34, s17, s30
	s_cselect_b32 s31, s19, s44
	s_cselect_b32 s30, s25, s27
	ds_read_b128 v[108:111], v251
	ds_read_b128 v[112:115], v251 offset:1024
	ds_read_b128 v[124:127], v251 offset:2048
	ds_read_b128 v[128:131], v251 offset:3072
	ds_read_b128 v[132:135], v251 offset:16384
	ds_read_b128 v[140:143], v251 offset:17408
	ds_read_b128 v[148:151], v251 offset:18432
	ds_read_b128 v[156:159], v251 offset:19456
	v_lshl_add_u64 v[212:213], s[28:29], 0, v[208:209]
	s_add_i32 m0, s42, 0xc000
	ds_read_b128 v[164:167], v253
	ds_read_b128 v[168:171], v253 offset:1024
	ds_read_b128 v[172:175], v253 offset:2048
	ds_read_b128 v[176:179], v253 offset:3072
	ds_read_b128 v[180:183], v253 offset:4096
	ds_read_b128 v[184:187], v253 offset:5120
	ds_read_b128 v[188:191], v253 offset:6144
	ds_read_b128 v[192:195], v253 offset:7168
	global_load_lds_dwordx4 v[212:213], off
	s_add_i32 m0, s42, 0xe000
	v_lshl_add_u64 v[212:213], s[28:29], 0, v[210:211]
	global_load_lds_dwordx4 v[212:213], off
	s_waitcnt vmcnt(26) lgkmcnt(0)
	s_barrier
	s_setprio 1
	v_mfma_f32_16x16x32_bf16 v[160:163], v[108:111], v[164:167], 0
	v_mfma_f32_16x16x32_bf16 v[152:155], v[124:127], v[164:167], 0
	v_mfma_f32_16x16x32_bf16 v[120:123], v[108:111], v[172:175], 0
	v_mfma_f32_16x16x32_bf16 v[116:119], v[124:127], v[172:175], 0
	v_mfma_f32_16x16x32_bf16 v[96:99], v[108:111], v[180:183], 0
	v_mfma_f32_16x16x32_bf16 v[92:95], v[124:127], v[180:183], 0
	v_mfma_f32_16x16x32_bf16 v[80:83], v[108:111], v[188:191], 0
	v_mfma_f32_16x16x32_bf16 v[76:79], v[124:127], v[188:191], 0
	v_mfma_f32_16x16x32_bf16 v[160:163], v[112:115], v[168:171], v[160:163]
	v_mfma_f32_16x16x32_bf16 v[152:155], v[128:131], v[168:171], v[152:155]
	v_mfma_f32_16x16x32_bf16 v[120:123], v[112:115], v[176:179], v[120:123]
	v_mfma_f32_16x16x32_bf16 v[116:119], v[128:131], v[176:179], v[116:119]
	v_mfma_f32_16x16x32_bf16 v[96:99], v[112:115], v[184:187], v[96:99]
	v_mfma_f32_16x16x32_bf16 v[92:95], v[128:131], v[184:187], v[92:95]
	v_mfma_f32_16x16x32_bf16 v[80:83], v[112:115], v[192:195], v[80:83]
	v_mfma_f32_16x16x32_bf16 v[76:79], v[128:131], v[192:195], v[76:79]
	s_setprio 0
	s_setprio 1
	v_mfma_f32_16x16x32_bf16 v[144:147], v[132:135], v[164:167], 0
	v_mfma_f32_16x16x32_bf16 v[136:139], v[148:151], v[164:167], 0
	v_mfma_f32_16x16x32_bf16 v[104:107], v[132:135], v[172:175], 0
	v_mfma_f32_16x16x32_bf16 v[100:103], v[148:151], v[172:175], 0
	v_mfma_f32_16x16x32_bf16 v[88:91], v[132:135], v[180:183], 0
	v_mfma_f32_16x16x32_bf16 v[84:87], v[148:151], v[180:183], 0
	v_mfma_f32_16x16x32_bf16 v[72:75], v[132:135], v[188:191], 0
	v_mfma_f32_16x16x32_bf16 v[68:71], v[148:151], v[188:191], 0
	v_mfma_f32_16x16x32_bf16 v[144:147], v[140:143], v[168:171], v[144:147]
	v_mfma_f32_16x16x32_bf16 v[136:139], v[156:159], v[168:171], v[136:139]
	v_mfma_f32_16x16x32_bf16 v[104:107], v[140:143], v[176:179], v[104:107]
	v_mfma_f32_16x16x32_bf16 v[100:103], v[156:159], v[176:179], v[100:103]
	v_mfma_f32_16x16x32_bf16 v[88:91], v[140:143], v[184:187], v[88:91]
	v_mfma_f32_16x16x32_bf16 v[84:87], v[156:159], v[184:187], v[84:87]
	v_mfma_f32_16x16x32_bf16 v[72:75], v[140:143], v[192:195], v[72:75]
	v_mfma_f32_16x16x32_bf16 v[68:71], v[156:159], v[192:195], v[68:71]
	s_setprio 0
	s_barrier
; #define PG8_STAGE(bufoff, gbase, voff) do { _Pragma("unroll") for (int _i = 0; _i < 2; ++_i) \
;         __builtin_amdgcn_global_load_lds((const unsigned*)((const char*)(gbase) + (voff)[_i]), (PG8_LAS unsigned*)(lds + (bufoff) + ldsw + _i * 8192), 16, 0, 0); } while (0)
; #define PG8_LDA(dst, b, h) do { _Pragma("unroll") for (int m = 0; m < 4; ++m) _Pragma("unroll") for (int k = 0; k < 2; ++k) dst[m][k] = *(const PG8_LAS bf16x8*)(lds + PG8_SA(b, h) + aoff + m * 2048 + k * 1024); } while (0)
; #define PG8_MMA(ai, bj, At, Bt) do { __builtin_amdgcn_s_setprio(1); _Pragma("unroll") for (int m = 0; m < 4; ++m) _Pragma("unroll") for (int n = 0; n < 2; ++n) _Pragma("unroll") for (int k = 0; k < 2; ++k) \
;         acc[ai][bj][m][n] = __builtin_amdgcn_mfma_f32_16x16x32_bf16(Bt[n][k], At[m][k], acc[ai][bj][m][n], 0, 0, 0); __builtin_amdgcn_s_setprio(0); } while (0)
; #define PG8_WAIT_V(n) asm volatile("s_waitcnt vmcnt(" #n ")" ::: "memory")
; #define PG8_WAIT_L(n) asm volatile("s_waitcnt lgkmcnt(" #n ")" ::: "memory")
; #define PG8_BAR __builtin_amdgcn_s_barrier()
; #define PG8_SCHED __builtin_amdgcn_sched_barrier(0)
; template <class Epi, class Sched, bool ALIGN_EPI = false, bool SP2 = false>
; __device__ __forceinline__ void gemm_phase(PG8_LAS unsigned char* lds, const Gemm g, const Sched& S, const Epi& E) {
;     ...
;             PG8_LDA(At, 0, 1); PG8_STAGE(PG8_SB(0, 0), b2, voffB); PG8_STAGE(PG8_SB(0, 1), b2 + hstep, voffB); PG8_STAGE(PG8_SA(0, 0), a2, voffA);
;             PG8_WAIT_V(8); PG8_WAIT_L(0); PG8_BAR; PG8_MMA(1, 0, At, B0); PG8_MMA(1, 1, At, B1); PG8_BAR; PG8_SCHED;
	v_lshl_add_u64 v[212:213], s[30:31], 0, v[202:203]
	s_add_i32 m0, s41, 0x10000
	ds_read_b128 v[164:167], v253 offset:16384
	ds_read_b128 v[168:171], v253 offset:17408
	ds_read_b128 v[172:175], v253 offset:18432
	ds_read_b128 v[176:179], v253 offset:19456
	ds_read_b128 v[180:183], v253 offset:20480
	ds_read_b128 v[184:187], v253 offset:21504
	ds_read_b128 v[188:191], v253 offset:22528
	ds_read_b128 v[192:195], v253 offset:23552
	global_load_lds_dwordx4 v[212:213], off
	s_add_i32 m0, s41, 0x12000
	s_add_u32 s52, s30, 0x40000
	v_lshl_add_u64 v[214:215], s[30:31], 0, v[206:207]
	s_addc_u32 s53, s31, 0
	global_load_lds_dwordx4 v[214:215], off
	v_lshl_add_u64 v[216:217], s[52:53], 0, v[202:203]
	s_add_i32 m0, s41, 0x14000
	v_lshl_add_u64 v[218:219], s[34:35], 0, v[204:205]
	global_load_lds_dwordx4 v[216:217], off
	s_add_i32 m0, s41, 0x16000
	v_lshl_add_u64 v[216:217], s[52:53], 0, v[206:207]
	global_load_lds_dwordx4 v[216:217], off
	s_mov_b32 m0, s42
	v_lshl_add_u64 v[216:217], s[34:35], 0, v[0:1]
	global_load_lds_dwordx4 v[216:217], off
	s_mov_b32 m0, s43
	s_add_i32 s52, 0, 0x18000
	global_load_lds_dwordx4 v[218:219], off
	s_waitcnt vmcnt(26) lgkmcnt(0)
	s_barrier
	s_setprio 1
	v_mfma_f32_16x16x32_bf16 v[64:67], v[108:111], v[164:167], 0
	v_mfma_f32_16x16x32_bf16 v[60:63], v[124:127], v[164:167], 0
	v_mfma_f32_16x16x32_bf16 v[48:51], v[108:111], v[172:175], 0
	v_mfma_f32_16x16x32_bf16 v[44:47], v[124:127], v[172:175], 0
	v_mfma_f32_16x16x32_bf16 v[32:35], v[108:111], v[180:183], 0
	v_mfma_f32_16x16x32_bf16 v[28:31], v[124:127], v[180:183], 0
	v_mfma_f32_16x16x32_bf16 v[16:19], v[108:111], v[188:191], 0
	v_mfma_f32_16x16x32_bf16 v[12:15], v[124:127], v[188:191], 0
	v_mfma_f32_16x16x32_bf16 v[64:67], v[112:115], v[168:171], v[64:67]
	v_mfma_f32_16x16x32_bf16 v[60:63], v[128:131], v[168:171], v[60:63]
	v_mfma_f32_16x16x32_bf16 v[48:51], v[112:115], v[176:179], v[48:51]
	v_mfma_f32_16x16x32_bf16 v[44:47], v[128:131], v[176:179], v[44:47]
	v_mfma_f32_16x16x32_bf16 v[32:35], v[112:115], v[184:187], v[32:35]
	v_mfma_f32_16x16x32_bf16 v[28:31], v[128:131], v[184:187], v[28:31]
	v_mfma_f32_16x16x32_bf16 v[16:19], v[112:115], v[192:195], v[16:19]
	v_mfma_f32_16x16x32_bf16 v[12:15], v[128:131], v[192:195], v[12:15]
	s_setprio 0
	s_setprio 1
	v_mfma_f32_16x16x32_bf16 v[56:59], v[132:135], v[164:167], 0
	v_mfma_f32_16x16x32_bf16 v[52:55], v[148:151], v[164:167], 0
	v_mfma_f32_16x16x32_bf16 v[40:43], v[132:135], v[172:175], 0
	v_mfma_f32_16x16x32_bf16 v[36:39], v[148:151], v[172:175], 0
	v_mfma_f32_16x16x32_bf16 v[24:27], v[132:135], v[180:183], 0
	v_mfma_f32_16x16x32_bf16 v[20:23], v[148:151], v[180:183], 0
	v_mfma_f32_16x16x32_bf16 v[8:11], v[132:135], v[188:191], 0
	v_mfma_f32_16x16x32_bf16 v[4:7], v[148:151], v[188:191], 0
	v_mfma_f32_16x16x32_bf16 v[56:59], v[140:143], v[168:171], v[56:59]
	v_mfma_f32_16x16x32_bf16 v[52:55], v[156:159], v[168:171], v[52:55]
	v_mfma_f32_16x16x32_bf16 v[40:43], v[140:143], v[176:179], v[40:43]
	v_mfma_f32_16x16x32_bf16 v[36:39], v[156:159], v[176:179], v[36:39]
	v_mfma_f32_16x16x32_bf16 v[24:27], v[140:143], v[184:187], v[24:27]
	v_mfma_f32_16x16x32_bf16 v[20:23], v[156:159], v[184:187], v[20:23]
	v_mfma_f32_16x16x32_bf16 v[8:11], v[140:143], v[192:195], v[8:11]
	v_mfma_f32_16x16x32_bf16 v[4:7], v[156:159], v[192:195], v[4:7]
	s_setprio 0
	s_barrier
	s_branch .Lkmid_1

; __device__ __forceinline__ int opaque_tid() { int t = (int)threadIdx.x; asm volatile("" : "+v"(t)); return t; }
; #define PG8_STAGE(bufoff, gbase, voff) do { _Pragma("unroll") for (int _i = 0; _i < 2; ++_i) \
;         __builtin_amdgcn_global_load_lds((const unsigned*)((const char*)(gbase) + (voff)[_i]), (PG8_LAS unsigned*)(lds + (bufoff) + ldsw + _i * 8192), 16, 0, 0); } while (0)
; template <class Epi, class Sched, bool ALIGN_EPI = false, bool SP2 = false>
; __device__ __forceinline__ void gemm_phase(PG8_LAS unsigned char* lds, const Gemm g, const Sched& S, const Epi& E) {
;     const int tid = opaque_tid(), wid = __builtin_amdgcn_readfirstlane(tid >> 6), lane = tid & 63, wr = wid >> 2, wc = wid & 3, fr = lane & 15, fq = lane >> 4;
;     const int K = g.K, nt = K / BK;
;     unsigned voffA[2], voffB[2];
; #pragma unroll
;     for (int i = 0; i < 2; ++i) { int R, C; stage_rc(tid * 16 + i * 8192, R, C); const int Rb = Epi::PERM ? ((R & ~31) + perm32(R & 31)) : R;
;         voffA[i] = (unsigned)(R * K + C) * 2u; voffB[i] = (unsigned)(Rb * K + C) * 2u; }
;     const size_t kstep = (size_t)(BK * 2);
;     const size_t hstep = (size_t)HALF * K * 2;
;     const size_t tstep = 2 * hstep;
;     const unsigned ldsw = (unsigned)wid * 1024u;
;     const int aoff = lds_byte(wr * 64 + fr, fq * 8), boff = lds_byte(wc * 32 + fr, fq * 8);
;     ...
;     Unit cur, nxt; int ui = 0;
;     if (!S.next(0, cur)) return;
;     f32x4 acc[2][2][4][2];
; #pragma unroll
;     for (int a = 0; a < 2; ++a)
; #pragma unroll
;         for (int b = 0; b < 2; ++b)
; #pragma unroll
;             for (int m = 0; m < 4; ++m)
; #pragma unroll
;                 for (int n = 0; n < 2; ++n) acc[a][b][m][n] = (f32x4){0.f, 0.f, 0.f, 0.f};
;     bf16x8 At[4][2], B0[2][2], B1[2][2];
;     const char* cA = (const char*)g.A + (size_t)cur.pm * tstep; const char* cB = (const char*)g.Bt + (size_t)cur.pn * tstep;
;     S.a_ready(cur);
;     if constexpr (SP2) {
;         PG8_STAGE(PG8_SB(0, 0), cB, voffB); PG8_STAGE(PG8_SB(0, 1), cB + hstep, voffB); PG8_STAGE(PG8_SA(0, 0), cA, voffA); PG8_STAGE(PG8_SA(0, 1), cA + hstep, voffA);
;         if (wr == 1) PG8_BAR;
;         PG8_WAIT_V(2); PG8_BAR;
;         PG8_STAGE(PG8_SB(1, 0), cB + kstep, voffB); PG8_STAGE(PG8_SA(1, 0), cA + kstep, voffA); PG8_STAGE(PG8_SB(1, 1), cB + hstep + kstep, voffB);
;         PG8_WAIT_V(6); PG8_BAR;
.LBB0_399:
	s_add_u32 s12, s4, 0xa400000
	s_addc_u32 s13, s5, 0
	s_lshl_b32 s3, s3, 5
	s_and_b32 s17, s3, 0x60
	s_add_i32 m0, s37, 0x18000
	v_lshl_add_u64 v[10:11], v[10:11], 0, s[82:83]
	s_lshl_b32 s7, s16, 13
	s_lshl_b32 s20, s17, 7
	s_waitcnt vmcnt(2)
	s_barrier
	global_load_lds_dwordx4 v[10:11], off
	v_lshl_add_u64 v[8:9], v[8:9], 0, s[82:83]
	s_add_i32 m0, s37, 0x1a000
	s_add_i32 s41, s37, 0x8000
	s_add_i32 s42, s37, 0xa000
	global_load_lds_dwordx4 v[8:9], off
	v_lshl_add_u64 v[4:5], v[4:5], 0, s[82:83]
	s_mov_b32 m0, s41
	s_add_u32 s18, s24, 0x40080
	global_load_lds_dwordx4 v[4:5], off
	v_lshl_add_u64 v[4:5], v[6:7], 0, s[82:83]
	s_mov_b32 m0, s42
	s_addc_u32 s19, s25, 0
	global_load_lds_dwordx4 v[4:5], off
	s_add_i32 m0, s37, 0x1c000
	v_lshl_add_u64 v[4:5], s[18:19], 0, v[134:135]
	global_load_lds_dwordx4 v[4:5], off
	v_lshl_add_u64 v[4:5], s[18:19], 0, v[0:1]
	s_add_i32 m0, s37, 0x1e000
	v_bfe_u32 v6, v12, 4, 2
	global_load_lds_dwordx4 v[4:5], off
	v_and_b32_e32 v5, 15, v12
	v_lshlrev_b32_e32 v4, 4, v6
	v_lshlrev_b32_e32 v7, 2, v12
	v_lshl_or_b32 v3, s16, 6, v5
	v_lshl_or_b32 v5, v5, 6, v4
	v_and_b32_e32 v7, 32, v7
	v_bitop3_b32 v8, v5, s7, v7 bitop3:0xde
	v_bitop3_b32 v164, v5, s20, v7 bitop3:0xde
	v_add_u32_e32 v164, 0x10000, v164
	v_mov_b32_e32 v5, v2
	v_lshl_add_u64 v[4:5], s[4:5], 0, v[4:5]
	s_mov_b64 s[4:5], 0x1a600000
	v_lshl_add_u64 v[138:139], v[4:5], 0, s[4:5]
	v_lshlrev_b32_e32 v4, 14, v17
	v_and_b32_e32 v4, 0xffff8000, v4
	v_lshl_add_u32 v4, v16, 11, v4
	v_and_b32_e32 v5, 1, v17
	v_lshl_or_b32 v4, v5, 6, v4
	v_lshl_add_u32 v140, v18, 1, v4
	v_lshlrev_b32_e32 v4, 14, v13
	v_and_b32_e32 v4, 0xffff8000, v4
	s_waitcnt vmcnt(6)
	v_lshl_add_u32 v4, v14, 11, v4
	v_and_b32_e32 v5, 1, v13
	s_cmpk_lt_u32 s15, 0x100
	v_lshl_or_b32 v4, v5, 6, v4
	s_sext_i32_i16 s3, s14
	s_cselect_b64 s[14:15], -1, 0
	v_lshl_or_b32 v165, v6, 3, s17
	v_mov_b32_e32 v141, v2
	v_lshl_add_u32 v142, v15, 1, v4
	v_mov_b32_e32 v143, v2
	s_mov_b32 s72, 0
	v_add_u32_e32 v166, 0, v8
	s_waitcnt vmcnt(0)
	s_barrier
	s_branch .LBB0_402

; #define PG8_STAGE(bufoff, gbase, voff) do { _Pragma("unroll") for (int _i = 0; _i < 2; ++_i) \
;         __builtin_amdgcn_global_load_lds((const unsigned*)((const char*)(gbase) + (voff)[_i]), (PG8_LAS unsigned*)(lds + (bufoff) + ldsw + _i * 8192), 16, 0, 0); } while (0)
; #define PG8_LDA(dst, b, h) do { _Pragma("unroll") for (int m = 0; m < 4; ++m) _Pragma("unroll") for (int k = 0; k < 2; ++k) dst[m][k] = *(const PG8_LAS bf16x8*)(lds + PG8_SA(b, h) + aoff + m * 2048 + k * 1024); } while (0)
; #define PG8_LDB(dst, b, h) do { _Pragma("unroll") for (int n = 0; n < 2; ++n) _Pragma("unroll") for (int k = 0; k < 2; ++k) dst[n][k] = *(const PG8_LAS bf16x8*)(lds + PG8_SB(b, h) + boff + n * 2048 + k * 1024); } while (0)
; #define PG8_MMA(ai, bj, At, Bt) do { __builtin_amdgcn_s_setprio(1); _Pragma("unroll") for (int m = 0; m < 4; ++m) _Pragma("unroll") for (int n = 0; n < 2; ++n) _Pragma("unroll") for (int k = 0; k < 2; ++k) \
;         acc[ai][bj][m][n] = __builtin_amdgcn_mfma_f32_16x16x32_bf16(Bt[n][k], At[m][k], acc[ai][bj][m][n], 0, 0, 0); __builtin_amdgcn_s_setprio(0); } while (0)
; #define PG8_WAIT_V(n) asm volatile("s_waitcnt vmcnt(" #n ")" ::: "memory")
; #define PG8_WAIT_L(n) asm volatile("s_waitcnt lgkmcnt(" #n ")" ::: "memory")
; #define PG8_BAR __builtin_amdgcn_s_barrier()
; template <class Epi, class Sched, bool ALIGN_EPI = false, bool SP2 = false>
; __device__ __forceinline__ void gemm_phase(PG8_LAS unsigned char* lds, const Gemm g, const Sched& S, const Epi& E) {
;     ...
;         const bool has_next = S.next(ui + 1, nxt);
;         const char* nA = has_next ? (const char*)g.A + (size_t)nxt.pm * tstep : cA; const char* nB = has_next ? (const char*)g.Bt + (size_t)nxt.pn * tstep : cB;
;         for (int t = 0; t < nt; t += 2) {
;             const bool last = (t == nt - 2);
;             const char* a1 = cA + (size_t)(t + 1) * kstep;
;             const char* a2 = last ? nA : cA + (size_t)(t + 2) * kstep; const char* b2 = last ? nB : cB + (size_t)(t + 2) * kstep;
;             const char* a3 = a2 + kstep; const char* b3 = b2 + kstep;
;             if (last && has_next) S.a_ready(nxt);
;             if constexpr (SP2) {
;             PG8_LDB(B0, 0, 0); PG8_LDB(B1, 0, 1); PG8_SCHED; PG8_LDA(At, 0, 0); PG8_STAGE(PG8_SA(1, 1), a1 + hstep, voffA);
;             PG8_WAIT_V(8); PG8_WAIT_L(0); PG8_BAR; PG8_MMA(0, 0, At, B0); PG8_MMA(0, 1, At, B1); PG8_BAR; PG8_SCHED;
.LBB0_404:
	s_ashr_i32 s17, s16, 31
	s_lshl_b64 s[20:21], s[16:17], 19
	s_add_u32 s20, s29, s20
	s_addc_u32 s21, s30, s21
	s_and_b64 s[22:23], s[4:5], exec
	s_cselect_b32 s7, s21, s9
	s_cselect_b32 s17, s20, s8
	s_ashr_i32 s19, s18, 31
	s_lshl_b64 s[22:23], s[18:19], 19
	s_add_u32 s22, s31, s22
	s_addc_u32 s23, s34, s23
	s_and_b64 s[26:27], s[4:5], exec
	s_cselect_b32 s19, s23, s25
	s_cselect_b32 s43, s22, s24
	s_add_u32 s8, s8, 0x40080
	s_addc_u32 s9, s9, 0
	s_add_u32 s44, s24, 0x100
	s_addc_u32 s45, s25, 0
	s_mov_b32 s46, -2
	s_add_u32 s24, s8, 0xfffc0080
	s_addc_u32 s25, s9, -1
	s_cmp_eq_u32 s46, 12
	s_cselect_b32 s27, s7, s25
	s_cselect_b32 s26, s17, s24
	s_cselect_b32 s25, s19, s45
	s_cselect_b32 s24, s43, s44
	s_add_i32 s50, 0, 0x14000
	ds_read_b128 v[144:147], v164
	ds_read_b128 v[148:151], v164 offset:1024
	ds_read_b128 v[152:155], v164 offset:2048
	ds_read_b128 v[156:159], v164 offset:3072
	ds_read_b128 v[160:163], v164 offset:16384
	ds_read_b128 v[168:171], v164 offset:17408
	ds_read_b128 v[172:175], v164 offset:18432
	ds_read_b128 v[176:179], v164 offset:19456
	v_lshl_add_u64 v[198:199], s[8:9], 0, v[140:141]
	s_add_i32 m0, s37, 0xc000
	ds_read_b128 v[180:183], v166
	ds_read_b128 v[184:187], v166 offset:1024
	ds_read_b128 v[188:191], v166 offset:2048
	ds_read_b128 v[192:195], v166 offset:3072
	ds_read_b128 v[202:205], v166 offset:4096
	ds_read_b128 v[206:209], v166 offset:5120
	ds_read_b128 v[210:213], v166 offset:6144
	ds_read_b128 v[214:217], v166 offset:7168
	global_load_lds_dwordx4 v[198:199], off
	s_add_i32 m0, s37, 0xe000
	v_lshl_add_u64 v[198:199], s[8:9], 0, v[142:143]
	global_load_lds_dwordx4 v[198:199], off
	s_waitcnt vmcnt(16) lgkmcnt(0)
	s_barrier
	s_setprio 1
	v_mfma_f32_16x16x32_bf16 v[128:131], v[144:147], v[180:183], 0
	v_mfma_f32_16x16x32_bf16 v[120:123], v[152:155], v[180:183], 0
	v_mfma_f32_16x16x32_bf16 v[112:115], v[144:147], v[188:191], 0
	v_mfma_f32_16x16x32_bf16 v[104:107], v[152:155], v[188:191], 0
	v_mfma_f32_16x16x32_bf16 v[96:99], v[144:147], v[202:205], 0
	v_mfma_f32_16x16x32_bf16 v[88:91], v[152:155], v[202:205], 0
	v_mfma_f32_16x16x32_bf16 v[80:83], v[144:147], v[210:213], 0
	v_mfma_f32_16x16x32_bf16 v[72:75], v[152:155], v[210:213], 0
	v_mfma_f32_16x16x32_bf16 v[128:131], v[148:151], v[184:187], v[128:131]
	v_mfma_f32_16x16x32_bf16 v[120:123], v[156:159], v[184:187], v[120:123]
	v_mfma_f32_16x16x32_bf16 v[112:115], v[148:151], v[192:195], v[112:115]
	v_mfma_f32_16x16x32_bf16 v[104:107], v[156:159], v[192:195], v[104:107]
	v_mfma_f32_16x16x32_bf16 v[96:99], v[148:151], v[206:209], v[96:99]
	v_mfma_f32_16x16x32_bf16 v[88:91], v[156:159], v[206:209], v[88:91]
	v_mfma_f32_16x16x32_bf16 v[80:83], v[148:151], v[214:217], v[80:83]
	v_mfma_f32_16x16x32_bf16 v[72:75], v[156:159], v[214:217], v[72:75]
	s_setprio 0
	s_setprio 1
	v_mfma_f32_16x16x32_bf16 v[124:127], v[160:163], v[180:183], 0
	v_mfma_f32_16x16x32_bf16 v[116:119], v[172:175], v[180:183], 0
	v_mfma_f32_16x16x32_bf16 v[108:111], v[160:163], v[188:191], 0
	v_mfma_f32_16x16x32_bf16 v[100:103], v[172:175], v[188:191], 0
	v_mfma_f32_16x16x32_bf16 v[92:95], v[160:163], v[202:205], 0
	v_mfma_f32_16x16x32_bf16 v[84:87], v[172:175], v[202:205], 0
	v_mfma_f32_16x16x32_bf16 v[76:79], v[160:163], v[210:213], 0
	v_mfma_f32_16x16x32_bf16 v[68:71], v[172:175], v[210:213], 0
	v_mfma_f32_16x16x32_bf16 v[124:127], v[168:171], v[184:187], v[124:127]
	v_mfma_f32_16x16x32_bf16 v[116:119], v[176:179], v[184:187], v[116:119]
	v_mfma_f32_16x16x32_bf16 v[108:111], v[168:171], v[192:195], v[108:111]
	v_mfma_f32_16x16x32_bf16 v[100:103], v[176:179], v[192:195], v[100:103]
	v_mfma_f32_16x16x32_bf16 v[92:95], v[168:171], v[206:209], v[92:95]
	v_mfma_f32_16x16x32_bf16 v[84:87], v[176:179], v[206:209], v[84:87]
	v_mfma_f32_16x16x32_bf16 v[76:79], v[168:171], v[214:217], v[76:79]
	v_mfma_f32_16x16x32_bf16 v[68:71], v[176:179], v[214:217], v[68:71]
	s_setprio 0
	s_barrier
; #define PG8_STAGE(bufoff, gbase, voff) do { _Pragma("unroll") for (int _i = 0; _i < 2; ++_i) \
;         __builtin_amdgcn_global_load_lds((const unsigned*)((const char*)(gbase) + (voff)[_i]), (PG8_LAS unsigned*)(lds + (bufoff) + ldsw + _i * 8192), 16, 0, 0); } while (0)
; #define PG8_LDA(dst, b, h) do { _Pragma("unroll") for (int m = 0; m < 4; ++m) _Pragma("unroll") for (int k = 0; k < 2; ++k) dst[m][k] = *(const PG8_LAS bf16x8*)(lds + PG8_SA(b, h) + aoff + m * 2048 + k * 1024); } while (0)
; #define PG8_MMA(ai, bj, At, Bt) do { __builtin_amdgcn_s_setprio(1); _Pragma("unroll") for (int m = 0; m < 4; ++m) _Pragma("unroll") for (int n = 0; n < 2; ++n) _Pragma("unroll") for (int k = 0; k < 2; ++k) \
;         acc[ai][bj][m][n] = __builtin_amdgcn_mfma_f32_16x16x32_bf16(Bt[n][k], At[m][k], acc[ai][bj][m][n], 0, 0, 0); __builtin_amdgcn_s_setprio(0); } while (0)
; #define PG8_WAIT_V(n) asm volatile("s_waitcnt vmcnt(" #n ")" ::: "memory")
; #define PG8_WAIT_L(n) asm volatile("s_waitcnt lgkmcnt(" #n ")" ::: "memory")
; #define PG8_BAR __builtin_amdgcn_s_barrier()
; #define PG8_SCHED __builtin_amdgcn_sched_barrier(0)
; template <class Epi, class Sched, bool ALIGN_EPI = false, bool SP2 = false>
; __device__ __forceinline__ void gemm_phase(PG8_LAS unsigned char* lds, const Gemm g, const Sched& S, const Epi& E) {
;     ...
;             PG8_LDA(At, 0, 1); PG8_STAGE(PG8_SB(0, 0), b2, voffB); PG8_STAGE(PG8_SB(0, 1), b2 + hstep, voffB); PG8_STAGE(PG8_SA(0, 0), a2, voffA);
;             PG8_WAIT_V(8); PG8_WAIT_L(0); PG8_BAR; PG8_MMA(1, 0, At, B0); PG8_MMA(1, 1, At, B1); PG8_BAR; PG8_SCHED;
	v_lshl_add_u64 v[198:199], s[24:25], 0, v[134:135]
	s_add_i32 m0, s35, 0x10000
	ds_read_b128 v[180:183], v166 offset:16384
	ds_read_b128 v[184:187], v166 offset:17408
	ds_read_b128 v[188:191], v166 offset:18432
	ds_read_b128 v[192:195], v166 offset:19456
	ds_read_b128 v[202:205], v166 offset:20480
	ds_read_b128 v[206:209], v166 offset:21504
	ds_read_b128 v[210:213], v166 offset:22528
	ds_read_b128 v[214:217], v166 offset:23552
	global_load_lds_dwordx4 v[198:199], off
	s_add_i32 m0, s35, 0x12000
	s_add_u32 s48, s24, 0x40000
	v_lshl_add_u64 v[218:219], s[24:25], 0, v[0:1]
	s_addc_u32 s49, s25, 0
	global_load_lds_dwordx4 v[218:219], off
	v_lshl_add_u64 v[220:221], s[48:49], 0, v[134:135]
	s_add_i32 m0, s35, 0x14000
	v_lshl_add_u64 v[222:223], s[26:27], 0, v[132:133]
	global_load_lds_dwordx4 v[220:221], off
	s_add_i32 m0, s35, 0x16000
	v_lshl_add_u64 v[220:221], s[48:49], 0, v[0:1]
	global_load_lds_dwordx4 v[220:221], off
	s_mov_b32 m0, s37
	v_lshl_add_u64 v[220:221], s[26:27], 0, v[136:137]
	global_load_lds_dwordx4 v[220:221], off
	s_mov_b32 m0, s38
	s_add_i32 s47, 0, 0x18000
	global_load_lds_dwordx4 v[222:223], off
	s_waitcnt vmcnt(16) lgkmcnt(0)
	s_barrier
	s_setprio 1
	v_mfma_f32_16x16x32_bf16 v[64:67], v[144:147], v[180:183], 0
	v_mfma_f32_16x16x32_bf16 v[56:59], v[152:155], v[180:183], 0
	v_mfma_f32_16x16x32_bf16 v[48:51], v[144:147], v[188:191], 0
	v_mfma_f32_16x16x32_bf16 v[40:43], v[152:155], v[188:191], 0
	v_mfma_f32_16x16x32_bf16 v[32:35], v[144:147], v[202:205], 0
	v_mfma_f32_16x16x32_bf16 v[24:27], v[152:155], v[202:205], 0
	v_mfma_f32_16x16x32_bf16 v[16:19], v[144:147], v[210:213], 0
	v_mfma_f32_16x16x32_bf16 v[8:11], v[152:155], v[210:213], 0
	v_mfma_f32_16x16x32_bf16 v[64:67], v[148:151], v[184:187], v[64:67]
	v_mfma_f32_16x16x32_bf16 v[56:59], v[156:159], v[184:187], v[56:59]
	v_mfma_f32_16x16x32_bf16 v[48:51], v[148:151], v[192:195], v[48:51]
	v_mfma_f32_16x16x32_bf16 v[40:43], v[156:159], v[192:195], v[40:43]
	v_mfma_f32_16x16x32_bf16 v[32:35], v[148:151], v[206:209], v[32:35]
	v_mfma_f32_16x16x32_bf16 v[24:27], v[156:159], v[206:209], v[24:27]
	v_mfma_f32_16x16x32_bf16 v[16:19], v[148:151], v[214:217], v[16:19]
	v_mfma_f32_16x16x32_bf16 v[8:11], v[156:159], v[214:217], v[8:11]
	s_setprio 0
	s_setprio 1
	v_mfma_f32_16x16x32_bf16 v[60:63], v[160:163], v[180:183], 0
	v_mfma_f32_16x16x32_bf16 v[52:55], v[172:175], v[180:183], 0
	v_mfma_f32_16x16x32_bf16 v[44:47], v[160:163], v[188:191], 0
	v_mfma_f32_16x16x32_bf16 v[36:39], v[172:175], v[188:191], 0
	v_mfma_f32_16x16x32_bf16 v[28:31], v[160:163], v[202:205], 0
	v_mfma_f32_16x16x32_bf16 v[20:23], v[172:175], v[202:205], 0
	v_mfma_f32_16x16x32_bf16 v[12:15], v[160:163], v[210:213], 0
	v_mfma_f32_16x16x32_bf16 v[4:7], v[172:175], v[210:213], 0
	v_mfma_f32_16x16x32_bf16 v[60:63], v[168:171], v[184:187], v[60:63]
	v_mfma_f32_16x16x32_bf16 v[52:55], v[176:179], v[184:187], v[52:55]
	v_mfma_f32_16x16x32_bf16 v[44:47], v[168:171], v[192:195], v[44:47]
	v_mfma_f32_16x16x32_bf16 v[36:39], v[176:179], v[192:195], v[36:39]
	v_mfma_f32_16x16x32_bf16 v[28:31], v[168:171], v[206:209], v[28:31]
	v_mfma_f32_16x16x32_bf16 v[20:23], v[176:179], v[206:209], v[20:23]
	v_mfma_f32_16x16x32_bf16 v[12:15], v[168:171], v[214:217], v[12:15]
	v_mfma_f32_16x16x32_bf16 v[4:7], v[176:179], v[214:217], v[4:7]
	s_setprio 0
	s_barrier
	s_branch .Lkmid_2

; #define PG8_STAGE(bufoff, gbase, voff) do { _Pragma("unroll") for (int _i = 0; _i < 2; ++_i) \
;         __builtin_amdgcn_global_load_lds((const unsigned*)((const char*)(gbase) + (voff)[_i]), (PG8_LAS unsigned*)(lds + (bufoff) + ldsw + _i * 8192), 16, 0, 0); } while (0)
; #define PG8_LDA(dst, b, h) do { _Pragma("unroll") for (int m = 0; m < 4; ++m) _Pragma("unroll") for (int k = 0; k < 2; ++k) dst[m][k] = *(const PG8_LAS bf16x8*)(lds + PG8_SA(b, h) + aoff + m * 2048 + k * 1024); } while (0)
; #define PG8_LDB(dst, b, h) do { _Pragma("unroll") for (int n = 0; n < 2; ++n) _Pragma("unroll") for (int k = 0; k < 2; ++k) dst[n][k] = *(const PG8_LAS bf16x8*)(lds + PG8_SB(b, h) + boff + n * 2048 + k * 1024); } while (0)
; #define PG8_MMA(ai, bj, At, Bt) do { __builtin_amdgcn_s_setprio(1); _Pragma("unroll") for (int m = 0; m < 4; ++m) _Pragma("unroll") for (int n = 0; n < 2; ++n) _Pragma("unroll") for (int k = 0; k < 2; ++k) \
;         acc[ai][bj][m][n] = __builtin_amdgcn_mfma_f32_16x16x32_bf16(Bt[n][k], At[m][k], acc[ai][bj][m][n], 0, 0, 0); __builtin_amdgcn_s_setprio(0); } while (0)
; #define PG8_WAIT_V(n) asm volatile("s_waitcnt vmcnt(" #n ")" ::: "memory")
; #define PG8_BAR __builtin_amdgcn_s_barrier()
; template <class Epi, class Sched, bool ALIGN_EPI = false, bool SP2 = false>
; __device__ __forceinline__ void gemm_phase(PG8_LAS unsigned char* lds, const Gemm g, const Sched& S, const Epi& E) {
;     ...
;         for (int t = 0; t < nt; t += 2) {
;             const bool last = (t == nt - 2);
;             const char* a1 = cA + (size_t)(t + 1) * kstep;
;             const char* a2 = last ? nA : cA + (size_t)(t + 2) * kstep; const char* b2 = last ? nB : cB + (size_t)(t + 2) * kstep;
;             const char* a3 = a2 + kstep; const char* b3 = b2 + kstep;
;             if (last && has_next) S.a_ready(nxt);
;             if constexpr (SP2) {
;             PG8_LDB(B0, 0, 0); PG8_LDB(B1, 0, 1); PG8_SCHED; PG8_LDA(At, 0, 0); PG8_STAGE(PG8_SA(1, 1), a1 + hstep, voffA);
;             PG8_WAIT_V(8); PG8_WAIT_L(0); PG8_BAR; PG8_MMA(0, 0, At, B0); PG8_MMA(0, 1, At, B1); PG8_BAR; PG8_SCHED;
;             PG8_LDA(At, 0, 1); PG8_STAGE(PG8_SB(0, 0), b2, voffB); PG8_STAGE(PG8_SB(0, 1), b2 + hstep, voffB); PG8_STAGE(PG8_SA(0, 0), a2, voffA);
;             PG8_WAIT_V(8); PG8_WAIT_L(0); PG8_BAR; PG8_MMA(1, 0, At, B0); PG8_MMA(1, 1, At, B1); PG8_BAR; PG8_SCHED;
.LBB0_479:
	s_add_u32 s44, s28, 0x100
	s_addc_u32 s45, s29, 0
	s_mov_b32 s53, -2
	s_add_u32 s8, s26, 0x100
	s_addc_u32 s9, s27, 0
	s_cmp_eq_u32 s53, 40
	s_cselect_b32 s31, s23, s9
	s_cselect_b32 s30, s22, s8
	s_cselect_b32 s29, s25, s45
	s_cselect_b32 s28, s24, s44
	ds_read_b128 v[68:71], v234
	ds_read_b128 v[80:83], v234 offset:1024
	ds_read_b128 v[92:95], v234 offset:2048
	ds_read_b128 v[100:103], v234 offset:3072
	ds_read_b128 v[112:115], v234 offset:16384
	ds_read_b128 v[120:123], v234 offset:17408
	ds_read_b128 v[132:135], v234 offset:18432
	ds_read_b128 v[144:147], v234 offset:19456
	v_lshl_add_u64 v[198:199], s[26:27], 0, v[204:205]
	s_add_i32 m0, s40, 0xc000
	ds_read_b128 v[156:159], v236
	ds_read_b128 v[168:171], v236 offset:1024
	ds_read_b128 v[172:175], v236 offset:2048
	ds_read_b128 v[176:179], v236 offset:3072
	ds_read_b128 v[180:183], v236 offset:4096
	ds_read_b128 v[184:187], v236 offset:5120
	ds_read_b128 v[188:191], v236 offset:6144
	ds_read_b128 v[208:211], v236 offset:7168
	global_load_lds_dwordx4 v[198:199], off
	s_add_i32 m0, s40, 0xe000
	v_lshl_add_u64 v[198:199], s[26:27], 0, v[206:207]
	global_load_lds_dwordx4 v[198:199], off
	s_waitcnt vmcnt(26) lgkmcnt(0)
	s_barrier
	s_setprio 1
	v_mfma_f32_16x16x32_bf16 v[164:167], v[68:71], v[156:159], 0
	v_mfma_f32_16x16x32_bf16 v[160:163], v[92:95], v[156:159], 0
	v_mfma_f32_16x16x32_bf16 v[140:143], v[68:71], v[172:175], 0
	v_mfma_f32_16x16x32_bf16 v[136:139], v[92:95], v[172:175], 0
	v_mfma_f32_16x16x32_bf16 v[116:119], v[68:71], v[180:183], 0
	v_mfma_f32_16x16x32_bf16 v[108:111], v[92:95], v[180:183], 0
	v_mfma_f32_16x16x32_bf16 v[88:91], v[68:71], v[188:191], 0
	v_mfma_f32_16x16x32_bf16 v[84:87], v[92:95], v[188:191], 0
	v_mfma_f32_16x16x32_bf16 v[164:167], v[80:83], v[168:171], v[164:167]
	v_mfma_f32_16x16x32_bf16 v[160:163], v[100:103], v[168:171], v[160:163]
	v_mfma_f32_16x16x32_bf16 v[140:143], v[80:83], v[176:179], v[140:143]
	v_mfma_f32_16x16x32_bf16 v[136:139], v[100:103], v[176:179], v[136:139]
	v_mfma_f32_16x16x32_bf16 v[116:119], v[80:83], v[184:187], v[116:119]
	v_mfma_f32_16x16x32_bf16 v[108:111], v[100:103], v[184:187], v[108:111]
	v_mfma_f32_16x16x32_bf16 v[88:91], v[80:83], v[208:211], v[88:91]
	v_mfma_f32_16x16x32_bf16 v[84:87], v[100:103], v[208:211], v[84:87]
	s_setprio 0
	s_setprio 1
	v_mfma_f32_16x16x32_bf16 v[152:155], v[112:115], v[156:159], 0
	v_mfma_f32_16x16x32_bf16 v[148:151], v[132:135], v[156:159], 0
	v_mfma_f32_16x16x32_bf16 v[128:131], v[112:115], v[172:175], 0
	v_mfma_f32_16x16x32_bf16 v[124:127], v[132:135], v[172:175], 0
	v_mfma_f32_16x16x32_bf16 v[104:107], v[112:115], v[180:183], 0
	v_mfma_f32_16x16x32_bf16 v[96:99], v[132:135], v[180:183], 0
	v_mfma_f32_16x16x32_bf16 v[76:79], v[112:115], v[188:191], 0
	v_mfma_f32_16x16x32_bf16 v[72:75], v[132:135], v[188:191], 0
	v_mfma_f32_16x16x32_bf16 v[152:155], v[120:123], v[168:171], v[152:155]
	v_mfma_f32_16x16x32_bf16 v[148:151], v[144:147], v[168:171], v[148:151]
	v_mfma_f32_16x16x32_bf16 v[128:131], v[120:123], v[176:179], v[128:131]
	v_mfma_f32_16x16x32_bf16 v[124:127], v[144:147], v[176:179], v[124:127]
	v_mfma_f32_16x16x32_bf16 v[104:107], v[120:123], v[184:187], v[104:107]
	v_mfma_f32_16x16x32_bf16 v[96:99], v[144:147], v[184:187], v[96:99]
	v_mfma_f32_16x16x32_bf16 v[76:79], v[120:123], v[208:211], v[76:79]
	v_mfma_f32_16x16x32_bf16 v[72:75], v[144:147], v[208:211], v[72:75]
	s_setprio 0
	s_barrier
	v_lshl_add_u64 v[198:199], s[28:29], 0, v[192:193]
	s_add_i32 m0, s39, 0x10000
	ds_read_b128 v[156:159], v236 offset:16384
	ds_read_b128 v[168:171], v236 offset:17408
	ds_read_b128 v[172:175], v236 offset:18432
	ds_read_b128 v[176:179], v236 offset:19456
	ds_read_b128 v[180:183], v236 offset:20480
	ds_read_b128 v[184:187], v236 offset:21504
	ds_read_b128 v[188:191], v236 offset:22528
	ds_read_b128 v[208:211], v236 offset:23552
	global_load_lds_dwordx4 v[198:199], off
	s_add_i32 m0, s39, 0x12000
	s_add_u32 s26, s28, 0xb0000
	v_lshl_add_u64 v[212:213], s[28:29], 0, v[202:203]
	s_addc_u32 s27, s29, 0
	global_load_lds_dwordx4 v[212:213], off
	v_lshl_add_u64 v[214:215], s[26:27], 0, v[192:193]
	s_add_i32 m0, s39, 0x14000
	v_lshl_add_u64 v[216:217], s[30:31], 0, v[194:195]
	global_load_lds_dwordx4 v[214:215], off
	s_add_i32 m0, s39, 0x16000
	v_lshl_add_u64 v[214:215], s[26:27], 0, v[202:203]
	global_load_lds_dwordx4 v[214:215], off
	s_mov_b32 m0, s40
	v_lshl_add_u64 v[214:215], s[30:31], 0, v[0:1]
	global_load_lds_dwordx4 v[214:215], off
	s_mov_b32 m0, s41
	s_add_i32 s54, 0, 0x18000
	global_load_lds_dwordx4 v[216:217], off
	s_waitcnt vmcnt(26) lgkmcnt(0)
	s_barrier
	s_setprio 1
	v_mfma_f32_16x16x32_bf16 v[64:67], v[68:71], v[156:159], 0
	v_mfma_f32_16x16x32_bf16 v[60:63], v[92:95], v[156:159], 0
	v_mfma_f32_16x16x32_bf16 v[48:51], v[68:71], v[172:175], 0
	v_mfma_f32_16x16x32_bf16 v[44:47], v[92:95], v[172:175], 0
	v_mfma_f32_16x16x32_bf16 v[32:35], v[68:71], v[180:183], 0
	v_mfma_f32_16x16x32_bf16 v[28:31], v[92:95], v[180:183], 0
	v_mfma_f32_16x16x32_bf16 v[16:19], v[68:71], v[188:191], 0
	v_mfma_f32_16x16x32_bf16 v[12:15], v[92:95], v[188:191], 0
	v_mfma_f32_16x16x32_bf16 v[64:67], v[80:83], v[168:171], v[64:67]
	v_mfma_f32_16x16x32_bf16 v[60:63], v[100:103], v[168:171], v[60:63]
	v_mfma_f32_16x16x32_bf16 v[48:51], v[80:83], v[176:179], v[48:51]
	v_mfma_f32_16x16x32_bf16 v[44:47], v[100:103], v[176:179], v[44:47]
	v_mfma_f32_16x16x32_bf16 v[32:35], v[80:83], v[184:187], v[32:35]
	v_mfma_f32_16x16x32_bf16 v[28:31], v[100:103], v[184:187], v[28:31]
	v_mfma_f32_16x16x32_bf16 v[16:19], v[80:83], v[208:211], v[16:19]
	v_mfma_f32_16x16x32_bf16 v[12:15], v[100:103], v[208:211], v[12:15]
	s_setprio 0
	s_setprio 1
	v_mfma_f32_16x16x32_bf16 v[56:59], v[112:115], v[156:159], 0
	v_mfma_f32_16x16x32_bf16 v[52:55], v[132:135], v[156:159], 0
	v_mfma_f32_16x16x32_bf16 v[40:43], v[112:115], v[172:175], 0
	v_mfma_f32_16x16x32_bf16 v[36:39], v[132:135], v[172:175], 0
	v_mfma_f32_16x16x32_bf16 v[24:27], v[112:115], v[180:183], 0
	v_mfma_f32_16x16x32_bf16 v[20:23], v[132:135], v[180:183], 0
	v_mfma_f32_16x16x32_bf16 v[8:11], v[112:115], v[188:191], 0
	v_mfma_f32_16x16x32_bf16 v[4:7], v[132:135], v[188:191], 0
	v_mfma_f32_16x16x32_bf16 v[56:59], v[120:123], v[168:171], v[56:59]
	v_mfma_f32_16x16x32_bf16 v[52:55], v[144:147], v[168:171], v[52:55]
	v_mfma_f32_16x16x32_bf16 v[40:43], v[120:123], v[176:179], v[40:43]
	v_mfma_f32_16x16x32_bf16 v[36:39], v[144:147], v[176:179], v[36:39]
	v_mfma_f32_16x16x32_bf16 v[24:27], v[120:123], v[184:187], v[24:27]
	v_mfma_f32_16x16x32_bf16 v[20:23], v[144:147], v[184:187], v[20:23]
	v_mfma_f32_16x16x32_bf16 v[8:11], v[120:123], v[208:211], v[8:11]
	v_mfma_f32_16x16x32_bf16 v[4:7], v[144:147], v[208:211], v[4:7]
	s_setprio 0
	s_barrier
	s_branch .Lkmid_3
